# adds: PEER pass 1 sweeps partitions 15..0 (starts on the slices pass 0 left in L2); GEMM2 epilogue ring moved to registers safe for multi-unit workgroups
# speedup vs baseline: 1.0119x; 1.0023x over previous
; __device__ __forceinline__ unsigned cvt_pk_bf16(float lo, float hi) { unsigned r; asm volatile("v_cvt_pk_bf16_f32 %0, %1, %2" : "=v"(r) : "v"(lo), "v"(hi)); return r; }
;     __device__ __forceinline__ void operator()(const f32x4 (&acc)[2][2][4][2], const Unit& u, int wr, int wc, int fr, int fq) const {
;     ...
;         const float* mp = mod + (size_t)((u.pm * BM) >> 11) * 6144;
;         f32x4 g1v[2][2], csv[2][2];
; #pragma unroll
;         for (int bj = 0; bj < 2; ++bj)
; #pragma unroll
;             for (int n = 0; n < 2; ++n) { const int c = col0 + bj * HALF + 4 * n; g1v[bj][n] = *(const f32x4*)(mp + 2048 + c); csv[bj][n] = *(const f32x4*)(ng + c) * (*(const f32x4*)(mp + 4096 + c) + 1.0f); }
; #pragma unroll
;         for (int ai = 0; ai < 2; ++ai)
; #pragma unroll
;             for (int m = 0; m < 4; ++m) { const int r = row0 + ai * HALF + m * 16; float ss = 0.f;
; #pragma unroll
;                 for (int bj = 0; bj < 2; ++bj) { const int c = col0 + bj * HALF;
;                     const f32x4 xa = *(const f32x4*)(x + (size_t)r * 1024 + c), xb = *(const f32x4*)(x + (size_t)r * 1024 + c + 4);
;                     const f32x4 v0 = xa + g1v[bj][0] * acc[ai][bj][m][0], v1 = xb + g1v[bj][1] * acc[ai][bj][m][1];
;                     *(f32x4*)(out + (size_t)r * 1024 + c) = v0; *(f32x4*)(out + (size_t)r * 1024 + c + 4) = v1;
;                     ss += (v0[0] * v0[0] + v0[1] * v0[1]) + (v0[2] * v0[2] + v0[3] * v0[3]) + (v1[0] * v1[0] + v1[1] * v1[1]) + (v1[2] * v1[2] + v1[3] * v1[3]);
;                     const f32x4 a0 = v0 * csv[bj][0], a1 = v1 * csv[bj][1];
;                     u32x4 w; w.x = cvt_pk_bf16(a0[0], a0[1]); w.y = cvt_pk_bf16(a0[2], a0[3]); w.z = cvt_pk_bf16(a1[0], a1[1]); w.w = cvt_pk_bf16(a1[2], a1[3]);
;                     *(u32x4*)(a3 + (size_t)r * 1024 + c) = w; }
;                 ss += __shfl_xor(ss, 16); ss += __shfl_xor(ss, 32);
;                 if (fq == 0) rs[(size_t)r * 16 + (u.pn & 3) * 4 + wc] = ss; }
.LBB0_548:
	s_ashr_i32 s27, s38, 3
	s_mul_hi_i32 s29, s27, 0x6000
	s_mulk_i32 s27, 0x6000
	s_add_u32 s27, s86, s27
	s_addc_u32 s29, s87, s29
	v_lshl_add_u32 v164, s38, 8, v175
	v_lshl_or_b32 v160, s0, 8, v177
	s_add_u32 s40, s27, 0x2000
	v_ashrrev_i32_e32 v165, 31, v164
	s_addc_u32 s41, s29, 0
	v_ashrrev_i32_e32 v161, 31, v160
	v_lshlrev_b64 v[88:89], 12, v[164:165]
	v_lshlrev_b64 v[162:163], 2, v[160:161]
	v_lshl_add_u64 v[74:75], s[52:53], 0, v[88:89]
	s_add_u32 s38, s27, 0x4000
	v_lshl_add_u64 v[72:73], s[40:41], 0, v[162:163]
	v_lshl_add_u64 v[216:217], v[74:75], 0, v[162:163]
	s_addc_u32 s39, s29, 0
	global_load_dwordx4 v[166:169], v[216:217], off
	global_load_dwordx4 v[76:79], v[72:73], off
	s_nop 0
	global_load_dwordx4 v[72:75], v[72:73], off offset:16
	s_nop 0
	global_load_dwordx4 v[170:173], v[216:217], off offset:16
	v_lshl_add_u64 v[90:91], s[38:39], 0, v[162:163]
	global_load_dwordx4 v[182:185], v[90:91], off
	global_load_dwordx4 v[186:189], v[90:91], off offset:16
	v_lshl_add_u64 v[90:91], s[36:37], 0, v[162:163]
	global_load_dwordx4 v[190:193], v[90:91], off
	global_load_dwordx4 v[194:197], v[90:91], off offset:16
	v_or_b32_e32 v92, 0x80, v160
	v_or_b32_e32 v94, 0x84, v160
	v_ashrrev_i32_e32 v93, 31, v92
	v_lshlrev_b64 v[198:199], 11, v[164:165]
	v_ashrrev_i32_e32 v95, 31, v94
	v_lshlrev_b64 v[92:93], 2, v[92:93]
	v_lshl_add_u64 v[88:89], s[48:49], 0, v[88:89]
	v_lshl_add_u64 v[206:207], s[10:11], 0, v[198:199]
	global_load_dwordx4 v[198:201], v[90:91], off offset:528
	global_load_dwordx4 v[202:205], v[90:91], off offset:512
	v_lshl_add_u64 v[218:219], v[88:89], 0, v[162:163]
	v_lshl_add_u64 v[220:221], v[160:161], 1, v[206:207]
	v_lshl_add_u64 v[88:89], s[40:41], 0, v[92:93]
	v_lshl_add_u64 v[90:91], v[94:95], 2, s[40:41]
	v_lshl_add_u64 v[210:211], s[38:39], 0, v[92:93]
	global_load_dwordx4 v[92:95], v[88:89], off
	global_load_dwordx4 v[206:209], v[210:211], off
	s_nop 0
	global_load_dwordx4 v[210:213], v[210:211], off offset:16
	s_nop 0
	global_load_dwordx4 v[88:91], v[90:91], off
	s_lshl_b32 s0, s0, 2
	s_and_b32 s27, s0, 12
	v_lshl_add_u32 v252, v164, 12, v162
	v_add_u32_e32 v253, 0x0, v252
	global_load_dwordx4 v[228:231], v253, s[52:53] offset:512
	global_load_dwordx4 v[232:235], v253, s[52:53] offset:528
	v_add_u32_e32 v253, 0x10000, v252
	global_load_dwordx4 v[236:239], v253, s[52:53]
	global_load_dwordx4 v[240:243], v253, s[52:53] offset:16
	global_load_dwordx4 v[244:247], v253, s[52:53] offset:512
	global_load_dwordx4 v[248:251], v253, s[52:53] offset:528
	s_waitcnt vmcnt(6)
	v_pk_fma_f32 v[166:167], v[140:141], v[76:77], v[166:167]
	v_pk_fma_f32 v[168:169], v[142:143], v[78:79], v[168:169]
	v_pk_fma_f32 v[170:171], v[136:137], v[72:73], v[170:171]
	v_pk_add_f32 v[136:137], v[184:185], 1.0 op_sel_hi:[1,0]
	v_pk_add_f32 v[140:141], v[182:183], 1.0 op_sel_hi:[1,0]
	v_pk_fma_f32 v[172:173], v[138:139], v[74:75], v[172:173]
	v_pk_add_f32 v[182:183], v[188:189], 1.0 op_sel_hi:[1,0]
	v_pk_add_f32 v[184:185], v[186:187], 1.0 op_sel_hi:[1,0]
	v_pk_mul_f32 v[138:139], v[192:193], v[136:137]
	v_pk_mul_f32 v[142:143], v[190:191], v[140:141]
	v_pk_mul_f32 v[136:137], v[196:197], v[182:183]
	v_pk_mul_f32 v[140:141], v[194:195], v[184:185]
	v_pk_mul_f32 v[184:185], v[138:139], v[168:169]
	v_pk_mul_f32 v[182:183], v[142:143], v[166:167]
	global_store_dwordx4 v[218:219], v[166:169], off
	global_store_dwordx4 v[218:219], v[170:173], off offset:16
	v_pk_mul_f32 v[186:187], v[136:137], v[172:173]
	v_pk_mul_f32 v[188:189], v[140:141], v[170:171]
	v_cvt_pk_bf16_f32 v182, v182, v183
	v_cvt_pk_bf16_f32 v183, v184, v185
	v_xor_b32_e32 v192, 32, v181
	v_cvt_pk_bf16_f32 v184, v188, v189
	v_cvt_pk_bf16_f32 v185, v186, v187
	global_store_dwordx4 v[220:221], v[182:185], off
	s_nop 0
	s_nop 0
	v_and_b32_e32 v183, 64, v181
	v_xor_b32_e32 v182, 16, v181
	v_add_u32_e32 v183, 64, v183
	v_cmp_lt_i32_e32 vcc, v182, v183
	v_mul_f32_e32 v215, v167, v167
	v_mul_f32_e32 v216, v169, v169
	v_cndmask_b32_e32 v182, v181, v182, vcc
	v_cmp_lt_i32_e32 vcc, v192, v183
	v_mul_f32_e32 v222, v173, v173
	v_mul_f32_e32 v217, v171, v171
	v_cndmask_b32_e32 v183, v181, v192, vcc
	v_pk_add_f32 v[192:193], v[208:209], 1.0 op_sel_hi:[1,0]
	v_fmac_f32_e32 v215, v166, v166
	v_fmac_f32_e32 v216, v168, v168
	v_fmac_f32_e32 v222, v172, v172
	v_pk_mul_f32 v[172:173], v[204:205], v[192:193]
	v_fmac_f32_e32 v217, v170, v170
	v_add_f32_e32 v192, v215, v216
	v_add_f32_e32 v192, v192, v217
	v_add_f32_e32 v192, v222, v192
	v_lshlrev_b32_e32 v182, 2, v182
	v_pk_add_f32 v[194:195], v[206:207], 1.0 op_sel_hi:[1,0]
	v_pk_add_f32 v[196:197], v[212:213], 1.0 op_sel_hi:[1,0]
	v_pk_add_f32 v[206:207], v[210:211], 1.0 op_sel_hi:[1,0]
	v_pk_mul_f32 v[166:167], v[200:201], v[196:197]
	v_pk_mul_f32 v[168:169], v[198:199], v[206:207]
	v_pk_mul_f32 v[170:171], v[202:203], v[194:195]
	s_waitcnt vmcnt(5)
	v_pk_fma_f32 v[134:135], v[134:135], v[94:95], v[230:231]
	v_pk_fma_f32 v[132:133], v[132:133], v[92:93], v[228:229]
	s_waitcnt vmcnt(4)
	v_pk_fma_f32 v[128:129], v[128:129], v[88:89], v[232:233]
	v_mul_f32_e32 v186, v133, v133
	v_mul_f32_e32 v187, v135, v135
	v_pk_fma_f32 v[130:131], v[130:131], v[90:91], v[234:235]
	v_add_u32_e32 v253, 0x20000, v252
	global_load_dwordx4 v[228:231], v253, s[52:53]
	global_load_dwordx4 v[232:235], v253, s[52:53] offset:16
	v_mul_f32_e32 v188, v129, v129
	v_fmac_f32_e32 v186, v132, v132
	v_fmac_f32_e32 v187, v134, v134
	global_store_dwordx4 v[218:219], v[132:135], off offset:512
	global_store_dwordx4 v[218:219], v[128:131], off offset:528
	v_mul_f32_e32 v189, v131, v131
	v_pk_mul_f32 v[184:185], v[172:173], v[134:135]
	v_fmac_f32_e32 v188, v128, v128
	v_add_f32_e32 v134, v186, v187
	v_fmac_f32_e32 v189, v130, v130
	v_add_f32_e32 v134, v134, v188
	v_add_f32_e32 v134, v189, v134
	v_add_f32_e32 v188, v192, v134
	ds_bpermute_b32 v189, v182, v188
	v_pk_mul_f32 v[186:187], v[166:167], v[130:131]
	v_pk_mul_f32 v[134:135], v[168:169], v[128:129]
	v_lshlrev_b32_e32 v130, 2, v183
	v_pk_mul_f32 v[132:133], v[170:171], v[132:133]
	s_waitcnt lgkmcnt(0)
	v_add_f32_e32 v128, v188, v189
	ds_bpermute_b32 v129, v130, v128
	v_cvt_pk_bf16_f32 v132, v132, v133
	v_cvt_pk_bf16_f32 v133, v184, v185
	v_cvt_pk_bf16_f32 v134, v134, v135
	v_cvt_pk_bf16_f32 v135, v186, v187
	global_store_dwordx4 v[220:221], v[132:135], off offset:256
	s_and_saveexec_b64 s[38:39], s[6:7]
	s_cbranch_execz .LBB0_550
	v_lshlrev_b64 v[132:133], 6, v[164:165]
	v_lshl_add_u64 v[132:133], s[12:13], 0, v[132:133]
	s_lshl_b32 s0, s27, 2
	v_lshl_add_u64 v[132:133], v[132:133], 0, s[0:1]
	s_lshl_b32 s0, s64, 2
	v_lshl_add_u64 v[132:133], v[132:133], 0, s[0:1]
	s_waitcnt lgkmcnt(0)
	v_add_f32_e32 v128, v128, v129
	global_store_dword v[132:133], v128, off
; __device__ __forceinline__ unsigned cvt_pk_bf16(float lo, float hi) { unsigned r; asm volatile("v_cvt_pk_bf16_f32 %0, %1, %2" : "=v"(r) : "v"(lo), "v"(hi)); return r; }
;     __device__ __forceinline__ void operator()(const f32x4 (&acc)[2][2][4][2], const Unit& u, int wr, int wc, int fr, int fq) const {
;     ...
;             for (int m = 0; m < 4; ++m) { const int r = row0 + ai * HALF + m * 16; float ss = 0.f;
; #pragma unroll
;                 for (int bj = 0; bj < 2; ++bj) { const int c = col0 + bj * HALF;
;                     const f32x4 xa = *(const f32x4*)(x + (size_t)r * 1024 + c), xb = *(const f32x4*)(x + (size_t)r * 1024 + c + 4);
;                     const f32x4 v0 = xa + g1v[bj][0] * acc[ai][bj][m][0], v1 = xb + g1v[bj][1] * acc[ai][bj][m][1];
;                     *(f32x4*)(out + (size_t)r * 1024 + c) = v0; *(f32x4*)(out + (size_t)r * 1024 + c + 4) = v1;
;                     ss += (v0[0] * v0[0] + v0[1] * v0[1]) + (v0[2] * v0[2] + v0[3] * v0[3]) + (v1[0] * v1[0] + v1[1] * v1[1]) + (v1[2] * v1[2] + v1[3] * v1[3]);
;                     const f32x4 a0 = v0 * csv[bj][0], a1 = v1 * csv[bj][1];
;                     u32x4 w; w.x = cvt_pk_bf16(a0[0], a0[1]); w.y = cvt_pk_bf16(a0[2], a0[3]); w.z = cvt_pk_bf16(a1[0], a1[1]); w.w = cvt_pk_bf16(a1[2], a1[3]);
;                     *(u32x4*)(a3 + (size_t)r * 1024 + c) = w; }
;                 ss += __shfl_xor(ss, 16); ss += __shfl_xor(ss, 32);
;                 if (fq == 0) rs[(size_t)r * 16 + (u.pn & 3) * 4 + wc] = ss; }
.LBB0_550:
	s_or_b64 exec, exec, s[38:39]
	v_or_b32_e32 v128, 16, v164
	s_waitcnt lgkmcnt(0)
	v_ashrrev_i32_e32 v129, 31, v128
	v_lshlrev_b64 v[188:189], 12, v[128:129]
	v_lshl_add_u64 v[132:133], s[52:53], 0, v[188:189]
	v_lshl_add_u64 v[190:191], v[132:133], 0, v[162:163]
	s_nop 0
	s_nop 0
	v_lshlrev_b64 v[192:193], 11, v[128:129]
	v_lshl_add_u64 v[188:189], s[48:49], 0, v[188:189]
	v_lshl_add_u64 v[192:193], s[10:11], 0, v[192:193]
	v_lshl_add_u64 v[188:189], v[188:189], 0, v[162:163]
	v_lshl_add_u64 v[192:193], v[160:161], 1, v[192:193]
	s_waitcnt vmcnt(5)
	v_pk_fma_f32 v[126:127], v[126:127], v[78:79], v[238:239]
	v_pk_fma_f32 v[124:125], v[124:125], v[76:77], v[236:237]
	s_waitcnt vmcnt(4)
	v_pk_fma_f32 v[122:123], v[122:123], v[74:75], v[242:243]
	v_pk_fma_f32 v[120:121], v[120:121], v[72:73], v[240:241]
	v_add_u32_e32 v253, 0x20000, v252
	global_load_dwordx4 v[236:239], v253, s[52:53] offset:512
	global_load_dwordx4 v[240:243], v253, s[52:53] offset:528
	v_pk_mul_f32 v[134:135], v[138:139], v[126:127]
	v_pk_mul_f32 v[132:133], v[142:143], v[124:125]
	global_store_dwordx4 v[188:189], v[124:127], off
	global_store_dwordx4 v[188:189], v[120:123], off offset:16
	v_pk_mul_f32 v[184:185], v[136:137], v[122:123]
	v_pk_mul_f32 v[186:187], v[140:141], v[120:121]
	v_cvt_pk_bf16_f32 v132, v132, v133
	v_cvt_pk_bf16_f32 v133, v134, v135
	v_mul_f32_e32 v125, v125, v125
	v_cvt_pk_bf16_f32 v134, v186, v187
	v_cvt_pk_bf16_f32 v135, v184, v185
	global_store_dwordx4 v[192:193], v[132:135], off
	s_nop 0
	s_nop 0
	v_mul_f32_e32 v127, v127, v127
	v_mul_f32_e32 v121, v121, v121
	v_fmac_f32_e32 v125, v124, v124
	v_fmac_f32_e32 v127, v126, v126
	v_mul_f32_e32 v123, v123, v123
	v_fmac_f32_e32 v121, v120, v120
	v_add_f32_e32 v120, v125, v127
	v_fmac_f32_e32 v123, v122, v122
	v_add_f32_e32 v120, v120, v121
	v_add_f32_e32 v120, v123, v120
	s_waitcnt vmcnt(5)
	v_pk_fma_f32 v[118:119], v[118:119], v[94:95], v[246:247]
	v_pk_fma_f32 v[116:117], v[116:117], v[92:93], v[244:245]
	s_waitcnt vmcnt(4)
	v_pk_fma_f32 v[112:113], v[112:113], v[88:89], v[248:249]
	v_mul_f32_e32 v121, v117, v117
	v_mul_f32_e32 v122, v119, v119
	v_pk_fma_f32 v[114:115], v[114:115], v[90:91], v[250:251]
	v_add_u32_e32 v253, 0x30000, v252
	global_load_dwordx4 v[244:247], v253, s[52:53]
	global_load_dwordx4 v[248:251], v253, s[52:53] offset:16
	v_mul_f32_e32 v123, v113, v113
	v_fmac_f32_e32 v121, v116, v116
	v_fmac_f32_e32 v122, v118, v118
	v_mul_f32_e32 v124, v115, v115
	v_fmac_f32_e32 v123, v112, v112
	v_add_f32_e32 v121, v121, v122
	v_fmac_f32_e32 v124, v114, v114
	v_add_f32_e32 v121, v121, v123
	v_add_f32_e32 v121, v124, v121
	v_add_f32_e32 v124, v120, v121
	ds_bpermute_b32 v125, v182, v124
	global_store_dwordx4 v[188:189], v[116:119], off offset:512
	global_store_dwordx4 v[188:189], v[112:115], off offset:528
	v_pk_mul_f32 v[122:123], v[168:169], v[112:113]
	v_pk_mul_f32 v[116:117], v[170:171], v[116:117]
	v_pk_mul_f32 v[118:119], v[172:173], v[118:119]
	s_waitcnt lgkmcnt(0)
	v_add_f32_e32 v112, v124, v125
	ds_bpermute_b32 v113, v130, v112
	v_pk_mul_f32 v[120:121], v[166:167], v[114:115]
	v_cvt_pk_bf16_f32 v114, v116, v117
	v_cvt_pk_bf16_f32 v115, v118, v119
	v_cvt_pk_bf16_f32 v116, v122, v123
	s_nop 0
	v_cvt_pk_bf16_f32 v117, v120, v121
	global_store_dwordx4 v[192:193], v[114:117], off offset:256
	s_and_saveexec_b64 s[38:39], s[6:7]
	s_cbranch_execz .LBB0_552
	v_lshlrev_b64 v[114:115], 6, v[128:129]
	v_lshl_add_u64 v[114:115], s[12:13], 0, v[114:115]
	s_lshl_b32 s0, s27, 2
	v_lshl_add_u64 v[114:115], v[114:115], 0, s[0:1]
	s_lshl_b32 s0, s64, 2
	v_lshl_add_u64 v[114:115], v[114:115], 0, s[0:1]
	s_waitcnt lgkmcnt(0)
	v_add_f32_e32 v112, v112, v113
	global_store_dword v[114:115], v112, off
.LBB0_552:
	s_or_b64 exec, exec, s[38:39]
	v_or_b32_e32 v112, 32, v164
	s_waitcnt lgkmcnt(0)
	v_ashrrev_i32_e32 v113, 31, v112
	v_lshlrev_b64 v[122:123], 12, v[112:113]
	v_lshl_add_u64 v[114:115], s[52:53], 0, v[122:123]
	v_lshl_add_u64 v[124:125], v[114:115], 0, v[162:163]
	s_nop 0
	s_nop 0
	v_lshlrev_b64 v[126:127], 11, v[112:113]
	v_lshl_add_u64 v[122:123], s[48:49], 0, v[122:123]
	v_lshl_add_u64 v[126:127], s[10:11], 0, v[126:127]
	v_lshl_add_u64 v[122:123], v[122:123], 0, v[162:163]
	v_lshl_add_u64 v[126:127], v[160:161], 1, v[126:127]
	s_waitcnt vmcnt(5)
	v_pk_fma_f32 v[110:111], v[110:111], v[78:79], v[230:231]
	v_pk_fma_f32 v[108:109], v[108:109], v[76:77], v[228:229]
	s_waitcnt vmcnt(4)
	v_pk_fma_f32 v[106:107], v[106:107], v[74:75], v[234:235]
	v_pk_fma_f32 v[104:105], v[104:105], v[72:73], v[232:233]
	v_add_u32_e32 v253, 0x30000, v252
	global_load_dwordx4 v[228:231], v253, s[52:53] offset:512
	global_load_dwordx4 v[232:235], v253, s[52:53] offset:528
	v_pk_mul_f32 v[116:117], v[138:139], v[110:111]
	v_pk_mul_f32 v[114:115], v[142:143], v[108:109]
	global_store_dwordx4 v[122:123], v[108:111], off
	global_store_dwordx4 v[122:123], v[104:107], off offset:16
	v_pk_mul_f32 v[118:119], v[136:137], v[106:107]
	v_pk_mul_f32 v[120:121], v[140:141], v[104:105]
	v_cvt_pk_bf16_f32 v114, v114, v115
	v_cvt_pk_bf16_f32 v115, v116, v117
	v_mul_f32_e32 v109, v109, v109
	v_cvt_pk_bf16_f32 v116, v120, v121
	v_cvt_pk_bf16_f32 v117, v118, v119
	global_store_dwordx4 v[126:127], v[114:117], off
	s_nop 0
	s_nop 0
	v_mul_f32_e32 v111, v111, v111
	v_mul_f32_e32 v105, v105, v105
	v_fmac_f32_e32 v109, v108, v108
	v_fmac_f32_e32 v111, v110, v110
	v_mul_f32_e32 v107, v107, v107
	v_fmac_f32_e32 v105, v104, v104
	v_add_f32_e32 v104, v109, v111
	v_fmac_f32_e32 v107, v106, v106
	v_add_f32_e32 v104, v104, v105
	v_add_f32_e32 v104, v107, v104
	s_waitcnt vmcnt(5)
; __device__ __forceinline__ unsigned cvt_pk_bf16(float lo, float hi) { unsigned r; asm volatile("v_cvt_pk_bf16_f32 %0, %1, %2" : "=v"(r) : "v"(lo), "v"(hi)); return r; }
;     __device__ __forceinline__ void operator()(const f32x4 (&acc)[2][2][4][2], const Unit& u, int wr, int wc, int fr, int fq) const {
;     ...
;             for (int m = 0; m < 4; ++m) { const int r = row0 + ai * HALF + m * 16; float ss = 0.f;
; #pragma unroll
;                 for (int bj = 0; bj < 2; ++bj) { const int c = col0 + bj * HALF;
;                     const f32x4 xa = *(const f32x4*)(x + (size_t)r * 1024 + c), xb = *(const f32x4*)(x + (size_t)r * 1024 + c + 4);
;                     const f32x4 v0 = xa + g1v[bj][0] * acc[ai][bj][m][0], v1 = xb + g1v[bj][1] * acc[ai][bj][m][1];
;                     *(f32x4*)(out + (size_t)r * 1024 + c) = v0; *(f32x4*)(out + (size_t)r * 1024 + c + 4) = v1;
;                     ss += (v0[0] * v0[0] + v0[1] * v0[1]) + (v0[2] * v0[2] + v0[3] * v0[3]) + (v1[0] * v1[0] + v1[1] * v1[1]) + (v1[2] * v1[2] + v1[3] * v1[3]);
;                     const f32x4 a0 = v0 * csv[bj][0], a1 = v1 * csv[bj][1];
;                     u32x4 w; w.x = cvt_pk_bf16(a0[0], a0[1]); w.y = cvt_pk_bf16(a0[2], a0[3]); w.z = cvt_pk_bf16(a1[0], a1[1]); w.w = cvt_pk_bf16(a1[2], a1[3]);
;                     *(u32x4*)(a3 + (size_t)r * 1024 + c) = w; }
;                 ss += __shfl_xor(ss, 16); ss += __shfl_xor(ss, 32);
;                 if (fq == 0) rs[(size_t)r * 16 + (u.pn & 3) * 4 + wc] = ss; }
	v_pk_fma_f32 v[102:103], v[102:103], v[94:95], v[238:239]
	v_pk_fma_f32 v[100:101], v[100:101], v[92:93], v[236:237]
	s_waitcnt vmcnt(4)
	v_pk_fma_f32 v[96:97], v[96:97], v[88:89], v[240:241]
	v_mul_f32_e32 v105, v101, v101
	v_mul_f32_e32 v106, v103, v103
	v_pk_fma_f32 v[98:99], v[98:99], v[90:91], v[242:243]
	v_add_u32_e32 v253, 0x80000, v252
	global_load_dwordx4 v[236:239], v253, s[52:53]
	global_load_dwordx4 v[240:243], v253, s[52:53] offset:16
	v_mul_f32_e32 v107, v97, v97
	v_fmac_f32_e32 v105, v100, v100
	v_fmac_f32_e32 v106, v102, v102
	v_mul_f32_e32 v108, v99, v99
	v_fmac_f32_e32 v107, v96, v96
	v_add_f32_e32 v105, v105, v106
	v_fmac_f32_e32 v108, v98, v98
	v_add_f32_e32 v105, v105, v107
	v_add_f32_e32 v105, v108, v105
	v_add_f32_e32 v108, v104, v105
	ds_bpermute_b32 v109, v182, v108
	global_store_dwordx4 v[122:123], v[100:103], off offset:512
	global_store_dwordx4 v[122:123], v[96:99], off offset:528
	v_pk_mul_f32 v[106:107], v[168:169], v[96:97]
	v_pk_mul_f32 v[100:101], v[170:171], v[100:101]
	v_pk_mul_f32 v[102:103], v[172:173], v[102:103]
	s_waitcnt lgkmcnt(0)
	v_add_f32_e32 v96, v108, v109
	ds_bpermute_b32 v97, v130, v96
	v_pk_mul_f32 v[104:105], v[166:167], v[98:99]
	v_cvt_pk_bf16_f32 v98, v100, v101
	v_cvt_pk_bf16_f32 v99, v102, v103
	v_cvt_pk_bf16_f32 v100, v106, v107
	s_nop 0
	v_cvt_pk_bf16_f32 v101, v104, v105
	global_store_dwordx4 v[126:127], v[98:101], off offset:256
	s_and_saveexec_b64 s[38:39], s[6:7]
	s_cbranch_execz .LBB0_554
	v_lshlrev_b64 v[98:99], 6, v[112:113]
	v_lshl_add_u64 v[98:99], s[12:13], 0, v[98:99]
	s_lshl_b32 s0, s27, 2
	v_lshl_add_u64 v[98:99], v[98:99], 0, s[0:1]
	s_lshl_b32 s0, s64, 2
	v_lshl_add_u64 v[98:99], v[98:99], 0, s[0:1]
	s_waitcnt lgkmcnt(0)
	v_add_f32_e32 v96, v96, v97
	global_store_dword v[98:99], v96, off
.LBB0_554:
	s_or_b64 exec, exec, s[38:39]
	v_or_b32_e32 v96, 48, v164
	s_waitcnt lgkmcnt(0)
	v_ashrrev_i32_e32 v97, 31, v96
	v_lshlrev_b64 v[106:107], 12, v[96:97]
	v_lshl_add_u64 v[98:99], s[52:53], 0, v[106:107]
	v_lshl_add_u64 v[108:109], v[98:99], 0, v[162:163]
	s_nop 0
	s_nop 0
	v_lshlrev_b64 v[110:111], 11, v[96:97]
	v_lshl_add_u64 v[106:107], s[48:49], 0, v[106:107]
	v_lshl_add_u64 v[110:111], s[10:11], 0, v[110:111]
	v_lshl_add_u64 v[106:107], v[106:107], 0, v[162:163]
	v_lshl_add_u64 v[110:111], v[160:161], 1, v[110:111]
	s_waitcnt vmcnt(5)
	v_pk_fma_f32 v[86:87], v[86:87], v[78:79], v[246:247]
	v_pk_fma_f32 v[84:85], v[84:85], v[76:77], v[244:245]
	s_waitcnt vmcnt(4)
	v_pk_fma_f32 v[82:83], v[82:83], v[74:75], v[250:251]
	v_pk_fma_f32 v[80:81], v[80:81], v[72:73], v[248:249]
	v_add_u32_e32 v253, 0x80000, v252
	global_load_dwordx4 v[244:247], v253, s[52:53] offset:512
	global_load_dwordx4 v[248:251], v253, s[52:53] offset:528
	v_pk_mul_f32 v[100:101], v[138:139], v[86:87]
	v_pk_mul_f32 v[98:99], v[142:143], v[84:85]
	global_store_dwordx4 v[106:107], v[84:87], off
	global_store_dwordx4 v[106:107], v[80:83], off offset:16
	v_pk_mul_f32 v[102:103], v[136:137], v[82:83]
	v_pk_mul_f32 v[104:105], v[140:141], v[80:81]
	v_cvt_pk_bf16_f32 v98, v98, v99
	v_cvt_pk_bf16_f32 v99, v100, v101
	v_mul_f32_e32 v85, v85, v85
	v_cvt_pk_bf16_f32 v100, v104, v105
	v_cvt_pk_bf16_f32 v101, v102, v103
	global_store_dwordx4 v[110:111], v[98:101], off
	s_nop 0
	s_nop 0
	v_mul_f32_e32 v87, v87, v87
	v_mul_f32_e32 v81, v81, v81
	v_fmac_f32_e32 v85, v84, v84
	v_fmac_f32_e32 v87, v86, v86
	v_mul_f32_e32 v83, v83, v83
	v_fmac_f32_e32 v81, v80, v80
	v_add_f32_e32 v80, v85, v87
	v_fmac_f32_e32 v83, v82, v82
	v_add_f32_e32 v80, v80, v81
	v_add_f32_e32 v80, v83, v80
	s_waitcnt vmcnt(5)
	v_pk_fma_f32 v[70:71], v[70:71], v[94:95], v[230:231]
	v_pk_fma_f32 v[68:69], v[68:69], v[92:93], v[228:229]
	s_waitcnt vmcnt(4)
	v_pk_fma_f32 v[64:65], v[64:65], v[88:89], v[232:233]
	v_mul_f32_e32 v81, v69, v69
	v_mul_f32_e32 v82, v71, v71
	v_pk_fma_f32 v[66:67], v[66:67], v[90:91], v[234:235]
	v_add_u32_e32 v253, 0x90000, v252
	global_load_dwordx4 v[228:231], v253, s[52:53]
	global_load_dwordx4 v[232:235], v253, s[52:53] offset:16
	v_mul_f32_e32 v83, v65, v65
	v_fmac_f32_e32 v81, v68, v68
	v_fmac_f32_e32 v82, v70, v70
	v_mul_f32_e32 v84, v67, v67
	v_fmac_f32_e32 v83, v64, v64
	v_add_f32_e32 v81, v81, v82
	v_fmac_f32_e32 v84, v66, v66
	v_add_f32_e32 v81, v81, v83
	v_add_f32_e32 v81, v84, v81
	v_add_f32_e32 v84, v80, v81
	ds_bpermute_b32 v85, v182, v84
	global_store_dwordx4 v[106:107], v[68:71], off offset:512
	global_store_dwordx4 v[106:107], v[64:67], off offset:528
	v_pk_mul_f32 v[82:83], v[168:169], v[64:65]
	v_pk_mul_f32 v[68:69], v[170:171], v[68:69]
	v_pk_mul_f32 v[70:71], v[172:173], v[70:71]
	s_waitcnt lgkmcnt(0)
	v_add_f32_e32 v64, v84, v85
	ds_bpermute_b32 v65, v130, v64
	v_pk_mul_f32 v[80:81], v[166:167], v[66:67]
	v_cvt_pk_bf16_f32 v66, v68, v69
	v_cvt_pk_bf16_f32 v67, v70, v71
	v_cvt_pk_bf16_f32 v68, v82, v83
	s_nop 0
	v_cvt_pk_bf16_f32 v69, v80, v81
	global_store_dwordx4 v[110:111], v[66:69], off offset:256
	s_and_saveexec_b64 s[38:39], s[6:7]
	s_cbranch_execz .LBB0_556
	v_lshlrev_b64 v[66:67], 6, v[96:97]
	v_lshl_add_u64 v[66:67], s[12:13], 0, v[66:67]
	s_lshl_b32 s0, s27, 2
	v_lshl_add_u64 v[66:67], v[66:67], 0, s[0:1]
	s_lshl_b32 s0, s64, 2
	v_lshl_add_u64 v[66:67], v[66:67], 0, s[0:1]
	s_waitcnt lgkmcnt(0)
	v_add_f32_e32 v64, v64, v65
	global_store_dword v[66:67], v64, off
; __device__ __forceinline__ unsigned cvt_pk_bf16(float lo, float hi) { unsigned r; asm volatile("v_cvt_pk_bf16_f32 %0, %1, %2" : "=v"(r) : "v"(lo), "v"(hi)); return r; }
;     __device__ __forceinline__ void operator()(const f32x4 (&acc)[2][2][4][2], const Unit& u, int wr, int wc, int fr, int fq) const {
;     ...
;             for (int m = 0; m < 4; ++m) { const int r = row0 + ai * HALF + m * 16; float ss = 0.f;
; #pragma unroll
;                 for (int bj = 0; bj < 2; ++bj) { const int c = col0 + bj * HALF;
;                     const f32x4 xa = *(const f32x4*)(x + (size_t)r * 1024 + c), xb = *(const f32x4*)(x + (size_t)r * 1024 + c + 4);
;                     const f32x4 v0 = xa + g1v[bj][0] * acc[ai][bj][m][0], v1 = xb + g1v[bj][1] * acc[ai][bj][m][1];
;                     *(f32x4*)(out + (size_t)r * 1024 + c) = v0; *(f32x4*)(out + (size_t)r * 1024 + c + 4) = v1;
;                     ss += (v0[0] * v0[0] + v0[1] * v0[1]) + (v0[2] * v0[2] + v0[3] * v0[3]) + (v1[0] * v1[0] + v1[1] * v1[1]) + (v1[2] * v1[2] + v1[3] * v1[3]);
;                     const f32x4 a0 = v0 * csv[bj][0], a1 = v1 * csv[bj][1];
;                     u32x4 w; w.x = cvt_pk_bf16(a0[0], a0[1]); w.y = cvt_pk_bf16(a0[2], a0[3]); w.z = cvt_pk_bf16(a1[0], a1[1]); w.w = cvt_pk_bf16(a1[2], a1[3]);
;                     *(u32x4*)(a3 + (size_t)r * 1024 + c) = w; }
;                 ss += __shfl_xor(ss, 16); ss += __shfl_xor(ss, 32);
;                 if (fq == 0) rs[(size_t)r * 16 + (u.pn & 3) * 4 + wc] = ss; }
.LBB0_556:
	s_or_b64 exec, exec, s[38:39]
	v_add_u32_e32 v64, 0x80, v164
	s_waitcnt lgkmcnt(0)
	v_ashrrev_i32_e32 v65, 31, v64
	v_lshlrev_b64 v[70:71], 12, v[64:65]
	v_lshl_add_u64 v[66:67], s[52:53], 0, v[70:71]
	v_lshl_add_u64 v[84:85], v[66:67], 0, v[162:163]
	s_nop 0
	s_nop 0
	v_lshlrev_b64 v[86:87], 11, v[64:65]
	v_lshl_add_u64 v[70:71], s[48:49], 0, v[70:71]
	v_lshl_add_u64 v[86:87], s[10:11], 0, v[86:87]
	v_lshl_add_u64 v[70:71], v[70:71], 0, v[162:163]
	v_lshl_add_u64 v[86:87], v[160:161], 1, v[86:87]
	s_waitcnt vmcnt(5)
	v_pk_fma_f32 v[62:63], v[62:63], v[78:79], v[238:239]
	v_pk_fma_f32 v[60:61], v[60:61], v[76:77], v[236:237]
	s_waitcnt vmcnt(4)
	v_pk_fma_f32 v[58:59], v[58:59], v[74:75], v[242:243]
	v_pk_fma_f32 v[56:57], v[56:57], v[72:73], v[240:241]
	v_add_u32_e32 v253, 0x90000, v252
	global_load_dwordx4 v[236:239], v253, s[52:53] offset:512
	global_load_dwordx4 v[240:243], v253, s[52:53] offset:528
	v_pk_mul_f32 v[68:69], v[138:139], v[62:63]
	v_pk_mul_f32 v[66:67], v[142:143], v[60:61]
	global_store_dwordx4 v[70:71], v[60:63], off
	global_store_dwordx4 v[70:71], v[56:59], off offset:16
	v_pk_mul_f32 v[80:81], v[136:137], v[58:59]
	v_pk_mul_f32 v[82:83], v[140:141], v[56:57]
	v_cvt_pk_bf16_f32 v66, v66, v67
	v_cvt_pk_bf16_f32 v67, v68, v69
	v_mul_f32_e32 v61, v61, v61
	v_cvt_pk_bf16_f32 v68, v82, v83
	v_cvt_pk_bf16_f32 v69, v80, v81
	global_store_dwordx4 v[86:87], v[66:69], off
	s_nop 0
	s_nop 0
	v_mul_f32_e32 v63, v63, v63
	v_mul_f32_e32 v57, v57, v57
	v_fmac_f32_e32 v61, v60, v60
	v_fmac_f32_e32 v63, v62, v62
	v_mul_f32_e32 v59, v59, v59
	v_fmac_f32_e32 v57, v56, v56
	v_add_f32_e32 v56, v61, v63
	v_fmac_f32_e32 v59, v58, v58
	v_add_f32_e32 v56, v56, v57
	v_add_f32_e32 v56, v59, v56
	s_waitcnt vmcnt(5)
	v_pk_fma_f32 v[54:55], v[54:55], v[94:95], v[246:247]
	v_pk_fma_f32 v[52:53], v[52:53], v[92:93], v[244:245]
	s_waitcnt vmcnt(4)
	v_pk_fma_f32 v[48:49], v[48:49], v[88:89], v[248:249]
	v_mul_f32_e32 v57, v53, v53
	v_mul_f32_e32 v58, v55, v55
	v_pk_fma_f32 v[50:51], v[50:51], v[90:91], v[250:251]
	v_add_u32_e32 v253, 0xa0000, v252
	global_load_dwordx4 v[244:247], v253, s[52:53]
	global_load_dwordx4 v[248:251], v253, s[52:53] offset:16
	v_mul_f32_e32 v59, v49, v49
	v_fmac_f32_e32 v57, v52, v52
	v_fmac_f32_e32 v58, v54, v54
	v_mul_f32_e32 v60, v51, v51
	v_fmac_f32_e32 v59, v48, v48
	v_add_f32_e32 v57, v57, v58
	v_fmac_f32_e32 v60, v50, v50
	v_add_f32_e32 v57, v57, v59
	v_add_f32_e32 v57, v60, v57
	v_add_f32_e32 v60, v56, v57
	ds_bpermute_b32 v61, v182, v60
	global_store_dwordx4 v[70:71], v[52:55], off offset:512
	global_store_dwordx4 v[70:71], v[48:51], off offset:528
	v_pk_mul_f32 v[58:59], v[168:169], v[48:49]
	v_pk_mul_f32 v[52:53], v[170:171], v[52:53]
	v_pk_mul_f32 v[54:55], v[172:173], v[54:55]
	s_waitcnt lgkmcnt(0)
	v_add_f32_e32 v48, v60, v61
	ds_bpermute_b32 v49, v130, v48
	v_pk_mul_f32 v[56:57], v[166:167], v[50:51]
	v_cvt_pk_bf16_f32 v50, v52, v53
	v_cvt_pk_bf16_f32 v51, v54, v55
	v_cvt_pk_bf16_f32 v52, v58, v59
	s_nop 0
	v_cvt_pk_bf16_f32 v53, v56, v57
	global_store_dwordx4 v[86:87], v[50:53], off offset:256
	s_and_saveexec_b64 s[38:39], s[6:7]
	s_cbranch_execz .LBB0_558
	v_lshlrev_b64 v[50:51], 6, v[64:65]
	v_lshl_add_u64 v[50:51], s[12:13], 0, v[50:51]
	s_lshl_b32 s0, s27, 2
	v_lshl_add_u64 v[50:51], v[50:51], 0, s[0:1]
	s_lshl_b32 s0, s64, 2
	v_lshl_add_u64 v[50:51], v[50:51], 0, s[0:1]
	s_waitcnt lgkmcnt(0)
	v_add_f32_e32 v48, v48, v49
	global_store_dword v[50:51], v48, off
; __device__ __forceinline__ unsigned cvt_pk_bf16(float lo, float hi) { unsigned r; asm volatile("v_cvt_pk_bf16_f32 %0, %1, %2" : "=v"(r) : "v"(lo), "v"(hi)); return r; }
;     __device__ __forceinline__ void operator()(const f32x4 (&acc)[2][2][4][2], const Unit& u, int wr, int wc, int fr, int fq) const {
;     ...
;             for (int m = 0; m < 4; ++m) { const int r = row0 + ai * HALF + m * 16; float ss = 0.f;
; #pragma unroll
;                 for (int bj = 0; bj < 2; ++bj) { const int c = col0 + bj * HALF;
;                     const f32x4 xa = *(const f32x4*)(x + (size_t)r * 1024 + c), xb = *(const f32x4*)(x + (size_t)r * 1024 + c + 4);
;                     const f32x4 v0 = xa + g1v[bj][0] * acc[ai][bj][m][0], v1 = xb + g1v[bj][1] * acc[ai][bj][m][1];
;                     *(f32x4*)(out + (size_t)r * 1024 + c) = v0; *(f32x4*)(out + (size_t)r * 1024 + c + 4) = v1;
;                     ss += (v0[0] * v0[0] + v0[1] * v0[1]) + (v0[2] * v0[2] + v0[3] * v0[3]) + (v1[0] * v1[0] + v1[1] * v1[1]) + (v1[2] * v1[2] + v1[3] * v1[3]);
;                     const f32x4 a0 = v0 * csv[bj][0], a1 = v1 * csv[bj][1];
;                     u32x4 w; w.x = cvt_pk_bf16(a0[0], a0[1]); w.y = cvt_pk_bf16(a0[2], a0[3]); w.z = cvt_pk_bf16(a1[0], a1[1]); w.w = cvt_pk_bf16(a1[2], a1[3]);
;                     *(u32x4*)(a3 + (size_t)r * 1024 + c) = w; }
;                 ss += __shfl_xor(ss, 16); ss += __shfl_xor(ss, 32);
;                 if (fq == 0) rs[(size_t)r * 16 + (u.pn & 3) * 4 + wc] = ss; }
.LBB0_558:
	s_or_b64 exec, exec, s[38:39]
	v_add_u32_e32 v48, 0x90, v164
	s_waitcnt lgkmcnt(0)
	v_ashrrev_i32_e32 v49, 31, v48
	v_lshlrev_b64 v[58:59], 12, v[48:49]
	v_lshl_add_u64 v[50:51], s[52:53], 0, v[58:59]
	v_lshl_add_u64 v[60:61], v[50:51], 0, v[162:163]
	s_nop 0
	s_nop 0
	v_lshlrev_b64 v[62:63], 11, v[48:49]
	v_lshl_add_u64 v[58:59], s[48:49], 0, v[58:59]
	v_lshl_add_u64 v[62:63], s[10:11], 0, v[62:63]
	v_lshl_add_u64 v[58:59], v[58:59], 0, v[162:163]
	v_lshl_add_u64 v[62:63], v[160:161], 1, v[62:63]
	s_waitcnt vmcnt(5)
	v_pk_fma_f32 v[46:47], v[46:47], v[78:79], v[230:231]
	v_pk_fma_f32 v[44:45], v[44:45], v[76:77], v[228:229]
	s_waitcnt vmcnt(4)
	v_pk_fma_f32 v[42:43], v[42:43], v[74:75], v[234:235]
	v_pk_fma_f32 v[40:41], v[40:41], v[72:73], v[232:233]
	v_add_u32_e32 v253, 0xa0000, v252
	global_load_dwordx4 v[228:231], v253, s[52:53] offset:512
	global_load_dwordx4 v[232:235], v253, s[52:53] offset:528
	v_pk_mul_f32 v[52:53], v[138:139], v[46:47]
	v_pk_mul_f32 v[50:51], v[142:143], v[44:45]
	global_store_dwordx4 v[58:59], v[44:47], off
	global_store_dwordx4 v[58:59], v[40:43], off offset:16
	v_pk_mul_f32 v[54:55], v[136:137], v[42:43]
	v_pk_mul_f32 v[56:57], v[140:141], v[40:41]
	v_cvt_pk_bf16_f32 v50, v50, v51
	v_cvt_pk_bf16_f32 v51, v52, v53
	v_mul_f32_e32 v45, v45, v45
	v_cvt_pk_bf16_f32 v52, v56, v57
	v_cvt_pk_bf16_f32 v53, v54, v55
	global_store_dwordx4 v[62:63], v[50:53], off
	s_nop 0
	s_nop 0
	v_mul_f32_e32 v47, v47, v47
	v_mul_f32_e32 v41, v41, v41
	v_fmac_f32_e32 v45, v44, v44
	v_fmac_f32_e32 v47, v46, v46
	v_mul_f32_e32 v43, v43, v43
	v_fmac_f32_e32 v41, v40, v40
	v_add_f32_e32 v40, v45, v47
	v_fmac_f32_e32 v43, v42, v42
	v_add_f32_e32 v40, v40, v41
	v_add_f32_e32 v40, v43, v40
	s_waitcnt vmcnt(5)
	v_pk_fma_f32 v[38:39], v[38:39], v[94:95], v[238:239]
	v_pk_fma_f32 v[36:37], v[36:37], v[92:93], v[236:237]
	s_waitcnt vmcnt(4)
	v_pk_fma_f32 v[32:33], v[32:33], v[88:89], v[240:241]
	v_mul_f32_e32 v41, v37, v37
	v_mul_f32_e32 v42, v39, v39
	v_pk_fma_f32 v[34:35], v[34:35], v[90:91], v[242:243]
	v_add_u32_e32 v253, 0xb0000, v252
	global_load_dwordx4 v[236:239], v253, s[52:53]
	global_load_dwordx4 v[240:243], v253, s[52:53] offset:16
	v_mul_f32_e32 v43, v33, v33
	v_fmac_f32_e32 v41, v36, v36
	v_fmac_f32_e32 v42, v38, v38
	v_mul_f32_e32 v44, v35, v35
	v_fmac_f32_e32 v43, v32, v32
	v_add_f32_e32 v41, v41, v42
	v_fmac_f32_e32 v44, v34, v34
	v_add_f32_e32 v41, v41, v43
	v_add_f32_e32 v41, v44, v41
	v_add_f32_e32 v44, v40, v41
	ds_bpermute_b32 v45, v182, v44
	global_store_dwordx4 v[58:59], v[36:39], off offset:512
	global_store_dwordx4 v[58:59], v[32:35], off offset:528
	v_pk_mul_f32 v[42:43], v[168:169], v[32:33]
	v_pk_mul_f32 v[36:37], v[170:171], v[36:37]
	v_pk_mul_f32 v[38:39], v[172:173], v[38:39]
	s_waitcnt lgkmcnt(0)
	v_add_f32_e32 v32, v44, v45
	ds_bpermute_b32 v33, v130, v32
	v_pk_mul_f32 v[40:41], v[166:167], v[34:35]
	v_cvt_pk_bf16_f32 v34, v36, v37
	v_cvt_pk_bf16_f32 v35, v38, v39
	v_cvt_pk_bf16_f32 v36, v42, v43
	s_nop 0
	v_cvt_pk_bf16_f32 v37, v40, v41
	global_store_dwordx4 v[62:63], v[34:37], off offset:256
	s_and_saveexec_b64 s[38:39], s[6:7]
	s_cbranch_execz .LBB0_560
	v_lshlrev_b64 v[34:35], 6, v[48:49]
	v_lshl_add_u64 v[34:35], s[12:13], 0, v[34:35]
	s_lshl_b32 s0, s27, 2
	v_lshl_add_u64 v[34:35], v[34:35], 0, s[0:1]
	s_lshl_b32 s0, s64, 2
	v_lshl_add_u64 v[34:35], v[34:35], 0, s[0:1]
	s_waitcnt lgkmcnt(0)
	v_add_f32_e32 v32, v32, v33
	global_store_dword v[34:35], v32, off
.LBB0_560:
	s_or_b64 exec, exec, s[38:39]
	v_add_u32_e32 v32, 0xa0, v164
	s_waitcnt lgkmcnt(0)
	v_ashrrev_i32_e32 v33, 31, v32
	v_lshlrev_b64 v[42:43], 12, v[32:33]
	v_lshl_add_u64 v[34:35], s[52:53], 0, v[42:43]
	v_lshl_add_u64 v[44:45], v[34:35], 0, v[162:163]
	s_nop 0
	s_nop 0
	v_lshlrev_b64 v[46:47], 11, v[32:33]
	v_lshl_add_u64 v[42:43], s[48:49], 0, v[42:43]
	v_lshl_add_u64 v[46:47], s[10:11], 0, v[46:47]
	v_lshl_add_u64 v[42:43], v[42:43], 0, v[162:163]
	v_lshl_add_u64 v[46:47], v[160:161], 1, v[46:47]
	s_waitcnt vmcnt(5)
	v_pk_fma_f32 v[30:31], v[30:31], v[78:79], v[246:247]
	v_pk_fma_f32 v[28:29], v[28:29], v[76:77], v[244:245]
	s_waitcnt vmcnt(4)
	v_pk_fma_f32 v[26:27], v[26:27], v[74:75], v[250:251]
	v_pk_fma_f32 v[24:25], v[24:25], v[72:73], v[248:249]
	v_add_u32_e32 v253, 0xb0000, v252
	global_load_dwordx4 v[244:247], v253, s[52:53] offset:512
	global_load_dwordx4 v[248:251], v253, s[52:53] offset:528
	v_pk_mul_f32 v[36:37], v[138:139], v[30:31]
	v_pk_mul_f32 v[34:35], v[142:143], v[28:29]
	global_store_dwordx4 v[42:43], v[28:31], off
	global_store_dwordx4 v[42:43], v[24:27], off offset:16
	v_pk_mul_f32 v[38:39], v[136:137], v[26:27]
	v_pk_mul_f32 v[40:41], v[140:141], v[24:25]
	v_cvt_pk_bf16_f32 v34, v34, v35
	v_cvt_pk_bf16_f32 v35, v36, v37
	v_mul_f32_e32 v29, v29, v29
	v_cvt_pk_bf16_f32 v36, v40, v41
	v_cvt_pk_bf16_f32 v37, v38, v39
	global_store_dwordx4 v[46:47], v[34:37], off
	s_nop 0
	s_nop 0
	v_mul_f32_e32 v31, v31, v31
	v_mul_f32_e32 v25, v25, v25
	v_fmac_f32_e32 v29, v28, v28
	v_fmac_f32_e32 v31, v30, v30
	v_mul_f32_e32 v27, v27, v27
	v_fmac_f32_e32 v25, v24, v24
	v_add_f32_e32 v24, v29, v31
	v_fmac_f32_e32 v27, v26, v26
	v_add_f32_e32 v24, v24, v25
	v_add_f32_e32 v24, v27, v24
	s_waitcnt vmcnt(5)
	v_pk_fma_f32 v[22:23], v[22:23], v[94:95], v[230:231]
	v_pk_fma_f32 v[20:21], v[20:21], v[92:93], v[228:229]
	s_waitcnt vmcnt(4)
	v_pk_fma_f32 v[16:17], v[16:17], v[88:89], v[232:233]
	v_mul_f32_e32 v25, v21, v21
	v_mul_f32_e32 v26, v23, v23
	v_pk_fma_f32 v[18:19], v[18:19], v[90:91], v[234:235]
	v_mul_f32_e32 v27, v17, v17
	v_fmac_f32_e32 v25, v20, v20
	v_fmac_f32_e32 v26, v22, v22
	v_mul_f32_e32 v28, v19, v19
	v_fmac_f32_e32 v27, v16, v16
	v_add_f32_e32 v25, v25, v26
	v_fmac_f32_e32 v28, v18, v18
	v_add_f32_e32 v25, v25, v27
	v_add_f32_e32 v25, v28, v25
	v_add_f32_e32 v28, v24, v25
	ds_bpermute_b32 v29, v182, v28
	global_store_dwordx4 v[42:43], v[20:23], off offset:512
	global_store_dwordx4 v[42:43], v[16:19], off offset:528
	v_pk_mul_f32 v[26:27], v[168:169], v[16:17]
	v_pk_mul_f32 v[20:21], v[170:171], v[20:21]
	v_pk_mul_f32 v[22:23], v[172:173], v[22:23]
	s_waitcnt lgkmcnt(0)
	v_add_f32_e32 v16, v28, v29
	ds_bpermute_b32 v17, v130, v16
	v_pk_mul_f32 v[24:25], v[166:167], v[18:19]
	v_cvt_pk_bf16_f32 v18, v20, v21
	v_cvt_pk_bf16_f32 v19, v22, v23
	v_cvt_pk_bf16_f32 v20, v26, v27
	s_nop 0
	v_cvt_pk_bf16_f32 v21, v24, v25
	global_store_dwordx4 v[46:47], v[18:21], off offset:256
	s_and_saveexec_b64 s[38:39], s[6:7]
	s_cbranch_execz .LBB0_562
	v_lshlrev_b64 v[18:19], 6, v[32:33]
	v_lshl_add_u64 v[18:19], s[12:13], 0, v[18:19]
	s_lshl_b32 s0, s27, 2
	v_lshl_add_u64 v[18:19], v[18:19], 0, s[0:1]
	s_lshl_b32 s0, s64, 2
	v_lshl_add_u64 v[18:19], v[18:19], 0, s[0:1]
	s_waitcnt lgkmcnt(0)
	v_add_f32_e32 v16, v16, v17
	global_store_dword v[18:19], v16, off

; __device__ __forceinline__ unsigned pk2(float lo, float hi) { const f32x2 v = {lo, hi}; const bf16x2_t b = __builtin_convertvector(v, bf16x2_t); return __builtin_bit_cast(unsigned, b); }
; __device__ __forceinline__ float bflo(unsigned u) { return __uint_as_float(u << 16); }
; __device__ __forceinline__ float bfhi(unsigned u) { return __uint_as_float(u & 0xffff0000u); }
; __device__ __forceinline__ void peer_tile(const Args& A, LAS unsigned char* lds, int tile) {
;     ...
;         const int tb = 8 * w + 4 * pass;
;         u32x4 xpa[4], xpb[4]; f32x2 oacc[4][8];
; #pragma unroll
;         for (int tk = 0; tk < 4; ++tk) { const size_t m = (size_t)tile * 64 + tb + tk;
;             { const u32x4 ra = *(const u32x4*)(A3 + m * 1024 + 16 * lane), rb = *(const u32x4*)(A3 + m * 1024 + 16 * lane + 8);
;               float xr_; { const f32x4 p0 = *(const f32x4*)(RSq + m * 16), p1 = *(const f32x4*)(RSq + m * 16 + 4), p2 = *(const f32x4*)(RSq + m * 16 + 8), p3 = *(const f32x4*)(RSq + m * 16 + 12);
;                 const f32x4 ps = (p0 + p1) + (p2 + p3); xr_ = rsqrtf(((ps[0] + ps[1]) + (ps[2] + ps[3])) * (1.f / 1024.f) + 1e-6f); }
;               const unsigned rr[8] = {ra.x, ra.y, ra.z, ra.w, rb.x, rb.y, rb.z, rb.w}; unsigned hh[8];
;               const float* sp = MOD + (int)(m >> 11) * 6144 + 3072 + 16 * lane;
; #pragma unroll
;               for (int q = 0; q < 8; ++q) { const f32x2 sh = *(const f32x2*)(sp + 2 * q); hh[q] = pk2(bflo(rr[q]) * xr_ + sh[0], bfhi(rr[q]) * xr_ + sh[1]); }
;               xpa[tk] = (u32x4){hh[0], hh[1], hh[2], hh[3]}; xpb[tk] = (u32x4){hh[4], hh[5], hh[6], hh[7]}; }
; #pragma unroll
;             for (int q = 0; q < 8; ++q) oacc[tk][q] = (f32x2){0.f, 0.f}; }
;         int it_p = 0, it_tk = -1, it_j = 0, it_end = 0; bool it_done = false;
.LBB0_799:
	s_mul_i32 s58, s3, 15
	s_lshr_b32 s58, s58, 2
	v_or_b32_e32 v126, s3, v222
	v_ashrrev_i32_e32 v127, 31, v126
	v_lshl_add_u64 v[124:125], s[28:29], 0, v[126:127]
	v_lshrrev_b32_e32 v0, 11, v124
	v_mul_u32_u24_e32 v1, 0x1800, v0
	v_mov_b32_e32 v0, v113
	v_ashrrev_i64 v[0:1], 30, v[0:1]
	v_lshl_add_u64 v[130:131], s[86:87], 0, v[0:1]
	v_lshlrev_b32_e32 v128, 2, v114
	v_mov_b32_e32 v129, v113
	v_lshlrev_b64 v[2:3], 11, v[124:125]
	v_lshl_add_u64 v[0:1], v[130:131], 0, v[128:129]
	v_lshl_add_u64 v[18:19], v[116:117], 0, v[2:3]
	v_lshlrev_b64 v[2:3], 6, v[124:125]
	v_lshl_add_u64 v[16:17], v[0:1], 0, s[14:15]
	v_lshl_add_u64 v[2:3], s[12:13], 0, v[2:3]
	v_add_co_u32_e32 v20, vcc, s39, v0
	global_load_dwordx4 v[88:91], v[2:3], off offset:32
	global_load_dwordx4 v[100:103], v[2:3], off offset:16
	global_load_dwordx4 v[44:47], v[18:19], off offset:16
	global_load_dwordx4 v[104:107], v[2:3], off
	v_addc_co_u32_e32 v21, vcc, 0, v1, vcc
	global_load_dwordx4 v[108:111], v[2:3], off offset:48
	global_load_dwordx4 v[12:15], v[20:21], off
	global_load_dwordx4 v[76:79], v[18:19], off
	s_nop 0
	global_load_dwordx4 v[0:3], v[16:17], off offset:48
	global_load_dwordx4 v[4:7], v[16:17], off offset:32
	global_load_dwordx4 v[8:11], v[16:17], off offset:16
	v_or_b32_e32 v16, 1, v124
	v_mov_b32_e32 v17, v125
	v_lshlrev_b64 v[18:19], 11, v[16:17]
	v_lshlrev_b64 v[16:17], 6, v[16:17]
	v_lshl_add_u64 v[18:19], v[116:117], 0, v[18:19]
	v_lshl_add_u64 v[16:17], s[12:13], 0, v[16:17]
	global_load_dwordx4 v[32:35], v[18:19], off offset:16
	global_load_dwordx4 v[48:51], v[18:19], off
	global_load_dwordx4 v[80:83], v[16:17], off offset:48
	global_load_dwordx4 v[84:87], v[16:17], off offset:32
	global_load_dwordx4 v[92:95], v[16:17], off offset:16
	global_load_dwordx4 v[96:99], v[16:17], off
	v_or_b32_e32 v16, 2, v124
	v_mov_b32_e32 v17, v125
	v_lshlrev_b64 v[18:19], 11, v[16:17]
	v_lshlrev_b64 v[16:17], 6, v[16:17]
	v_lshl_add_u64 v[18:19], v[116:117], 0, v[18:19]
	v_lshl_add_u64 v[16:17], s[12:13], 0, v[16:17]
	v_or_b32_e32 v36, 3, v124
	v_mov_b32_e32 v37, v125
	global_load_dwordx4 v[24:27], v[18:19], off offset:16
	global_load_dwordx4 v[28:31], v[18:19], off
	global_load_dwordx4 v[60:63], v[16:17], off offset:48
	global_load_dwordx4 v[64:67], v[16:17], off offset:32
	global_load_dwordx4 v[68:71], v[16:17], off offset:16
	global_load_dwordx4 v[72:75], v[16:17], off
	v_lshlrev_b64 v[16:17], 11, v[36:37]
	v_lshlrev_b64 v[36:37], 6, v[36:37]
	v_lshl_add_u64 v[38:39], v[116:117], 0, v[16:17]
	v_lshl_add_u64 v[56:57], s[12:13], 0, v[36:37]
	global_load_dwordx4 v[16:19], v[38:39], off offset:16
	global_load_dwordx4 v[20:23], v[38:39], off
	s_nop 0
	global_load_dwordx4 v[36:39], v[56:57], off offset:48
	global_load_dwordx4 v[40:43], v[56:57], off offset:32
	global_load_dwordx4 v[52:55], v[56:57], off offset:16
	s_nop 0
	global_load_dwordx4 v[56:59], v[56:57], off
	s_xor_b64 s[0:1], s[4:5], -1
	s_mov_b32 s3, -1
	s_mov_b32 s51, 0
	s_branch .LBB0_801
.LBB0_800:
	v_add_u32_e32 v112, s3, v126
	s_xor_b32 s4, s51, s58
	s_lshl_b32 s4, s4, 2
	v_mul_lo_u32 v112, v112, s38
	s_add_i32 s4, s4, 0
	v_add_u32_e32 v112, s4, v112
	v_add_u32_e32 v112, 0x21000, v112
	ds_read2_b32 v[132:133], v112 offset1:1
	s_mov_b64 s[4:5], 0
	s_mov_b32 s44, s51
	s_waitcnt lgkmcnt(0)
	v_readfirstlane_b32 s50, v132
	v_readfirstlane_b32 s45, v133
	s_cmp_lt_i32 s50, s45
	s_cselect_b64 s[30:31], -1, 0
	s_andn2_b64 vcc, exec, s[30:31]
	s_cbranch_vccz .LBB0_805

; __device__ __forceinline__ void peer_tile(const Args& A, LAS unsigned char* lds, int tile) {
;     ...
;         for (int p = 0; p < 16; ++p) {
; #pragma unroll
;             for (int tk = 0; tk < 4; ++tk) {
;                 const int tl = tb + tk;
;                 const int beg = __builtin_amdgcn_readfirstlane(OFFS[tl * 17 + p]), end = __builtin_amdgcn_readfirstlane(OFFS[tl * 17 + p + 1]);
.LBB0_807:
	s_xor_b32 s59, s51, s58
	v_lshl_add_u32 v129, s59, 2, v115
	ds_read2_b32 v[32:33], v129 offset1:1
	s_waitcnt lgkmcnt(0)
	v_readfirstlane_b32 s52, v32
	v_readfirstlane_b32 s53, v33
	s_cmp_ge_i32 s52, s53
	s_cbranch_scc0 .LBB0_809
	s_branch .LBB0_824

.LBB0_810:
	v_add_u32_e32 v32, s3, v126
	s_xor_b32 s4, s56, s58
	s_lshl_b32 s4, s4, 2
	v_mul_lo_u32 v32, v32, s38
	s_add_i32 s4, s4, 0
	v_add_u32_e32 v32, s4, v32
	v_add_u32_e32 v32, 0x21000, v32
	ds_read2_b32 v[32:33], v32 offset1:1
	s_mov_b64 s[4:5], 0
	s_mov_b32 s44, s56
	s_waitcnt lgkmcnt(0)
	v_readfirstlane_b32 s50, v32
	v_readfirstlane_b32 s45, v33
	s_cmp_lt_i32 s50, s45
	s_cselect_b64 s[30:31], -1, 0
	s_andn2_b64 vcc, exec, s[30:31]
	s_cbranch_vccz .LBB0_815

.LBB0_817:
	v_add_u32_e32 v0, s3, v126
	s_xor_b32 s4, s44, s58
	s_lshl_b32 s4, s4, 2
	v_mul_lo_u32 v0, v0, s38
	s_add_i32 s4, s4, 0
	v_add_u32_e32 v0, s4, v0
	v_add_u32_e32 v0, 0x21000, v0
	ds_read2_b32 v[0:1], v0 offset1:1
	s_mov_b64 s[4:5], 0
	s_mov_b32 s56, s44
	s_waitcnt lgkmcnt(0)
	v_readfirstlane_b32 s50, v0
	v_readfirstlane_b32 s45, v1
	s_cmp_lt_i32 s50, s45
	s_cselect_b64 s[30:31], -1, 0
	s_andn2_b64 vcc, exec, s[30:31]
	s_cbranch_vccz .LBB0_822
